# K/V global prefetch issued right after the tile barrier and next-tile LDS write moved to PV1 in the GQA and differential-attention loops
# speedup vs baseline: 1.0052x; 1.0052x over previous
.Lfar_p1_main:
	s_waitcnt lgkmcnt(5)
	v_mfma_f32_32x32x16_bf16 v[96:111], v[178:181], v[112:115], v[80:95]
	ds_read_b128 v[178:181], v175 offset:4672
	s_waitcnt lgkmcnt(5)
	v_mfma_f32_32x32x16_bf16 v[96:111], v[206:209], v[116:119], v[96:111]
	ds_read_b128 v[206:209], v175 offset:4704
	s_waitcnt lgkmcnt(5)
	v_mfma_f32_32x32x16_bf16 v[96:111], v[210:213], v[120:123], v[96:111]
	ds_read_b128 v[210:213], v175 offset:17408
	s_waitcnt lgkmcnt(5)
	v_mfma_f32_32x32x16_bf16 v[96:111], v[214:217], v[124:127], v[96:111]
	ds_read_b128 v[214:217], v175 offset:22016
	s_waitcnt lgkmcnt(5)
	v_mfma_f32_32x32x16_bf16 v[80:95], v[230:233], v[112:115], v[80:95]
	ds_read_b128 v[230:233], v175 offset:26624
	s_waitcnt lgkmcnt(5)
	v_mfma_f32_32x32x16_bf16 v[80:95], v[236:239], v[116:119], v[80:95]
	ds_read_b128 v[236:239], v175 offset:31232
	v_add_u32_e32 v185, s26, v194
	v_add3_u32 v184, s26, v192, v193
	v_add_u32_e32 v218, v185, v197
	v_add_u32_e32 v185, v185, v196
	s_nop 0
	v_exp_f32_e32 v96, v96
	v_exp_f32_e32 v97, v97
	v_exp_f32_e32 v98, v98
	s_waitcnt lgkmcnt(5)
	v_mfma_f32_32x32x16_bf16 v[80:95], v[178:181], v[120:123], v[80:95]
	ds_read_b128 v[178:181], v175 offset:17440
	v_exp_f32_e32 v99, v99
	v_exp_f32_e32 v100, v100
	v_exp_f32_e32 v101, v101
	s_waitcnt lgkmcnt(5)
	v_mfma_f32_32x32x16_bf16 v[80:95], v[206:209], v[124:127], v[80:95]
	ds_read_b128 v[206:209], v175 offset:22048
	v_exp_f32_e32 v102, v102
	v_exp_f32_e32 v103, v103
	v_cvt_pk_bf16_f32 v96, v96, v97
	v_cvt_pk_bf16_f32 v97, v98, v99
	v_cvt_pk_bf16_f32 v98, v100, v101
	v_cvt_pk_bf16_f32 v99, v102, v103
	s_nop 1
	v_mfma_f32_16x16x32_bf16 v[248:251], v[226:229], v[96:99], v[248:251]
	v_exp_f32_e32 v104, v104
	v_exp_f32_e32 v105, v105
	v_exp_f32_e32 v106, v106
	s_waitcnt lgkmcnt(5)
	v_mfma_f32_32x32x16_bf16 v[48:63], v[210:213], v[96:99], v[48:63]
	ds_read_b128 v[210:213], v175 offset:26656
	v_exp_f32_e32 v107, v107
	v_exp_f32_e32 v108, v108
	v_exp_f32_e32 v109, v109
	s_waitcnt lgkmcnt(5)
	v_mfma_f32_32x32x16_bf16 v[32:47], v[214:217], v[96:99], v[32:47]
	ds_read_b128 v[214:217], v175 offset:31264
	v_exp_f32_e32 v110, v110
	v_exp_f32_e32 v111, v111
	v_cvt_pk_bf16_f32 v104, v104, v105
	s_waitcnt lgkmcnt(5)
	v_mfma_f32_32x32x16_bf16 v[16:31], v[230:233], v[96:99], v[16:31]
	ds_read_b128 v[230:233], v175 offset:17472
	v_cvt_pk_bf16_f32 v105, v106, v107
	v_cvt_pk_bf16_f32 v106, v108, v109
	v_cvt_pk_bf16_f32 v107, v110, v111
	s_waitcnt lgkmcnt(5)
	v_mfma_f32_32x32x16_bf16 v[0:15], v[236:239], v[96:99], v[0:15]
	ds_read_b128 v[236:239], v175 offset:22080
	v_mfma_f32_16x16x32_bf16 v[248:251], v[226:229], v[104:107], v[248:251]
	v_exp_f32_e32 v80, v80
	v_exp_f32_e32 v81, v81
	v_exp_f32_e32 v82, v82
	s_waitcnt lgkmcnt(5)
	v_mfma_f32_32x32x16_bf16 v[48:63], v[178:181], v[104:107], v[48:63]
	ds_read_b128 v[178:181], v175 offset:26688
	s_waitcnt vmcnt(2)
	ds_write_b128 v184, v[128:131]
	v_exp_f32_e32 v83, v83
	v_exp_f32_e32 v84, v84
	v_exp_f32_e32 v85, v85
	s_waitcnt lgkmcnt(6)
	v_mfma_f32_32x32x16_bf16 v[32:47], v[206:209], v[104:107], v[32:47]
	ds_read_b128 v[206:209], v175 offset:31296
	s_waitcnt vmcnt(1)
	ds_write_b128 v185, v[132:135] offset:17408
	v_exp_f32_e32 v86, v86
	v_exp_f32_e32 v87, v87
	v_cvt_pk_bf16_f32 v80, v80, v81
	s_waitcnt lgkmcnt(7)
	v_mfma_f32_32x32x16_bf16 v[16:31], v[210:213], v[104:107], v[16:31]
	ds_read_b128 v[210:213], v175 offset:17504
	s_waitcnt vmcnt(0)
	ds_write_b128 v218, v[136:139] offset:17408
	v_cvt_pk_bf16_f32 v81, v82, v83
	v_cvt_pk_bf16_f32 v82, v84, v85
	v_cvt_pk_bf16_f32 v83, v86, v87
	s_waitcnt lgkmcnt(8)
	v_mfma_f32_32x32x16_bf16 v[0:15], v[214:217], v[104:107], v[0:15]
	ds_read_b128 v[214:217], v175 offset:22112
	s_waitcnt lgkmcnt(1)
	s_barrier
	s_add_i32 s28, s12, 64
	s_cmpk_eq_i32 s28, 0x2000
	s_cbranch_scc1 .Lfar_p1_tailnp
	s_add_i32 s30, s21, s28
	s_addk_i32 s30, 0x99
	s_cmpk_gt_u32 s30, 0x112
	s_cbranch_scc0 .Lfar_p1_tailnp
	s_cmpk_gt_u32 s13, 0x7d
	s_cbranch_scc1 .Lfar_p1_noloada
	global_load_dwordx4 v[128:131], v[190:191], off
	global_load_dwordx4 v[132:135], v[188:189], off
	global_load_dwordx4 v[136:139], v[186:187], off
.Lfar_p1_noloada:
	v_mfma_f32_16x16x32_bf16 v[248:251], v[226:229], v[80:83], v[248:251]
	v_exp_f32_e32 v88, v88
	v_exp_f32_e32 v89, v89
	v_exp_f32_e32 v90, v90
	v_mfma_f32_32x32x16_bf16 v[48:63], v[230:233], v[80:83], v[48:63]
	ds_read_b128 v[230:233], v175 offset:26720
	v_exp_f32_e32 v91, v91
	v_exp_f32_e32 v92, v92
	v_exp_f32_e32 v93, v93
	v_mfma_f32_32x32x16_bf16 v[32:47], v[236:239], v[80:83], v[32:47]
	ds_read_b128 v[236:239], v175 offset:31328
	v_exp_f32_e32 v94, v94
	v_exp_f32_e32 v95, v95
	v_cvt_pk_bf16_f32 v88, v88, v89
	v_mfma_f32_32x32x16_bf16 v[16:31], v[178:181], v[80:83], v[16:31]
	v_add_u32_e32 v175, s26, v198
	ds_read_b128 v[178:181], v175
	v_cvt_pk_bf16_f32 v89, v90, v91
	v_cvt_pk_bf16_f32 v90, v92, v93
	v_cvt_pk_bf16_f32 v91, v94, v95
	v_mfma_f32_32x32x16_bf16 v[0:15], v[206:209], v[80:83], v[0:15]
	ds_read_b128 v[206:209], v175 offset:32
	v_mfma_f32_16x16x32_bf16 v[248:251], v[226:229], v[88:91], v[248:251]
	s_add_i32 s12, s12, 64
	s_add_i32 s13, s13, 1
	v_mfma_f32_32x32x16_bf16 v[48:63], v[210:213], v[88:91], v[48:63]
	ds_read_b128 v[210:213], v175 offset:64
	v_lshl_add_u64 v[186:187], v[186:187], 0, s[72:73]
	s_waitcnt lgkmcnt(5)
	v_mfma_f32_32x32x16_bf16 v[32:47], v[214:217], v[88:91], v[32:47]
	ds_read_b128 v[214:217], v175 offset:96
	v_lshl_add_u64 v[188:189], v[188:189], 0, s[72:73]
	s_waitcnt lgkmcnt(5)
	v_mfma_f32_32x32x16_bf16 v[16:31], v[230:233], v[88:91], v[16:31]
	ds_read_b128 v[230:233], v175 offset:4608
	v_lshl_add_u64 v[190:191], v[190:191], 0, s[0:1]
	s_mov_b32 s27, s26
	s_waitcnt lgkmcnt(5)
	v_mfma_f32_32x32x16_bf16 v[0:15], v[236:239], v[88:91], v[0:15]
	ds_read_b128 v[236:239], v175 offset:4640
	s_add_i32 s26, s27, 0x8c00
	s_cmp_lg_u32 s27, 0x11800
	s_cselect_b32 s26, s26, 0
	s_cmp_gt_i32 s30, -1
	s_cselect_b64 vcc, -1, 0
	s_nop 1
	v_cndmask_b32_e32 v80, v204, v205, vcc
	v_mov_b32_e32 v81, v80
	v_mov_b32_e32 v82, v80
	v_mov_b32_e32 v83, v80
	v_mov_b32_e32 v84, v80
	v_mov_b32_e32 v85, v80
	v_mov_b32_e32 v86, v80
	v_mov_b32_e32 v87, v80
	v_mov_b32_e32 v88, v80
	v_mov_b32_e32 v89, v80
	v_mov_b32_e32 v90, v80
	v_mov_b32_e32 v91, v80
	v_mov_b32_e32 v92, v80
	v_mov_b32_e32 v93, v80
	v_mov_b32_e32 v94, v80
	v_mov_b32_e32 v95, v80
	s_nop 0
	s_branch .Lfar_p1_main
.Lfar_p1_tailnp:
	s_cmpk_gt_u32 s13, 0x7d
	s_cbranch_scc1 .Lfar_p1_noloadb
	global_load_dwordx4 v[128:131], v[190:191], off
	global_load_dwordx4 v[132:135], v[188:189], off
	global_load_dwordx4 v[136:139], v[186:187], off
.Lfar_p1_noloadb:
	v_mfma_f32_16x16x32_bf16 v[248:251], v[226:229], v[80:83], v[248:251]
	v_exp_f32_e32 v88, v88
	v_exp_f32_e32 v89, v89
	v_exp_f32_e32 v90, v90
	v_mfma_f32_32x32x16_bf16 v[48:63], v[230:233], v[80:83], v[48:63]
	ds_read_b128 v[230:233], v175 offset:26720
	v_exp_f32_e32 v91, v91
	v_exp_f32_e32 v92, v92
	v_exp_f32_e32 v93, v93
	v_mfma_f32_32x32x16_bf16 v[32:47], v[236:239], v[80:83], v[32:47]
	ds_read_b128 v[236:239], v175 offset:31328
	v_exp_f32_e32 v94, v94
	v_exp_f32_e32 v95, v95
	v_cvt_pk_bf16_f32 v88, v88, v89
	v_mfma_f32_32x32x16_bf16 v[16:31], v[178:181], v[80:83], v[16:31]
	v_cvt_pk_bf16_f32 v89, v90, v91
	v_cvt_pk_bf16_f32 v90, v92, v93
	v_cvt_pk_bf16_f32 v91, v94, v95
	v_mfma_f32_32x32x16_bf16 v[0:15], v[206:209], v[80:83], v[0:15]
	v_mfma_f32_16x16x32_bf16 v[248:251], v[226:229], v[88:91], v[248:251]
	s_add_i32 s12, s12, 64
	s_add_i32 s13, s13, 1
	v_mfma_f32_32x32x16_bf16 v[48:63], v[210:213], v[88:91], v[48:63]
	v_lshl_add_u64 v[186:187], v[186:187], 0, s[72:73]
	s_waitcnt lgkmcnt(2)
	v_mfma_f32_32x32x16_bf16 v[32:47], v[214:217], v[88:91], v[32:47]
	v_lshl_add_u64 v[188:189], v[188:189], 0, s[72:73]
	s_waitcnt lgkmcnt(1)
	v_mfma_f32_32x32x16_bf16 v[16:31], v[230:233], v[88:91], v[16:31]
	v_lshl_add_u64 v[190:191], v[190:191], 0, s[0:1]
	s_mov_b32 s27, s26
	s_waitcnt lgkmcnt(0)
	v_mfma_f32_32x32x16_bf16 v[0:15], v[236:239], v[88:91], v[0:15]
	s_cmpk_lg_i32 s12, 0x2000
	s_cbranch_scc0 .LBB0_1043
	s_branch .LBB0_1037

.Lfar_p2_main:
	s_waitcnt lgkmcnt(5)
	v_mfma_f32_32x32x16_bf16 v[96:111], v[178:181], v[112:115], v[80:95]
	ds_read_b128 v[178:181], v169 offset:4672
	s_waitcnt lgkmcnt(5)
	v_mfma_f32_32x32x16_bf16 v[96:111], v[206:209], v[116:119], v[96:111]
	ds_read_b128 v[206:209], v169 offset:4704
	s_waitcnt lgkmcnt(5)
	v_mfma_f32_32x32x16_bf16 v[96:111], v[210:213], v[120:123], v[96:111]
	ds_read_b128 v[210:213], v169 offset:17408
	s_waitcnt lgkmcnt(5)
	v_mfma_f32_32x32x16_bf16 v[96:111], v[214:217], v[124:127], v[96:111]
	ds_read_b128 v[214:217], v169 offset:22016
	s_waitcnt lgkmcnt(5)
	v_mfma_f32_32x32x16_bf16 v[80:95], v[230:233], v[112:115], v[80:95]
	ds_read_b128 v[230:233], v169 offset:26624
	s_waitcnt lgkmcnt(5)
	v_mfma_f32_32x32x16_bf16 v[80:95], v[236:239], v[116:119], v[80:95]
	ds_read_b128 v[236:239], v169 offset:31232
	v_add_u32_e32 v185, s12, v194
	v_add3_u32 v184, s12, v192, v193
	v_add_u32_e32 v218, v185, v197
	v_add_u32_e32 v185, v185, v196
	s_nop 0
	v_exp_f32_e32 v96, v96
	v_exp_f32_e32 v97, v97
	v_exp_f32_e32 v98, v98
	s_waitcnt lgkmcnt(5)
	v_mfma_f32_32x32x16_bf16 v[80:95], v[178:181], v[120:123], v[80:95]
	ds_read_b128 v[178:181], v169 offset:17440
	v_exp_f32_e32 v99, v99
	v_exp_f32_e32 v100, v100
	v_exp_f32_e32 v101, v101
	s_waitcnt lgkmcnt(5)
	v_mfma_f32_32x32x16_bf16 v[80:95], v[206:209], v[124:127], v[80:95]
	ds_read_b128 v[206:209], v169 offset:22048
	v_exp_f32_e32 v102, v102
	v_exp_f32_e32 v103, v103
	v_cvt_pk_bf16_f32 v96, v96, v97
	v_cvt_pk_bf16_f32 v97, v98, v99
	v_cvt_pk_bf16_f32 v98, v100, v101
	v_cvt_pk_bf16_f32 v99, v102, v103
	s_nop 1
	v_mfma_f32_16x16x32_bf16 v[248:251], v[226:229], v[96:99], v[248:251]
	v_exp_f32_e32 v104, v104
	v_exp_f32_e32 v105, v105
	v_exp_f32_e32 v106, v106
	s_waitcnt lgkmcnt(5)
	v_mfma_f32_32x32x16_bf16 v[48:63], v[210:213], v[96:99], v[48:63]
	ds_read_b128 v[210:213], v169 offset:26656
	v_exp_f32_e32 v107, v107
	v_exp_f32_e32 v108, v108
	v_exp_f32_e32 v109, v109
	s_waitcnt lgkmcnt(5)
	v_mfma_f32_32x32x16_bf16 v[32:47], v[214:217], v[96:99], v[32:47]
	ds_read_b128 v[214:217], v169 offset:31264
	v_exp_f32_e32 v110, v110
	v_exp_f32_e32 v111, v111
	v_cvt_pk_bf16_f32 v104, v104, v105
	s_waitcnt lgkmcnt(5)
	v_mfma_f32_32x32x16_bf16 v[16:31], v[230:233], v[96:99], v[16:31]
	ds_read_b128 v[230:233], v169 offset:17472
	v_cvt_pk_bf16_f32 v105, v106, v107
	v_cvt_pk_bf16_f32 v106, v108, v109
	v_cvt_pk_bf16_f32 v107, v110, v111
	s_waitcnt lgkmcnt(5)
	v_mfma_f32_32x32x16_bf16 v[0:15], v[236:239], v[96:99], v[0:15]
	ds_read_b128 v[236:239], v169 offset:22080
	v_mfma_f32_16x16x32_bf16 v[248:251], v[226:229], v[104:107], v[248:251]
	v_exp_f32_e32 v80, v80
	v_exp_f32_e32 v81, v81
	v_exp_f32_e32 v82, v82
	s_waitcnt lgkmcnt(5)
	v_mfma_f32_32x32x16_bf16 v[48:63], v[178:181], v[104:107], v[48:63]
	ds_read_b128 v[178:181], v169 offset:26688
	s_waitcnt vmcnt(2)
	ds_write_b128 v184, v[128:131]
	v_exp_f32_e32 v83, v83
	v_exp_f32_e32 v84, v84
	v_exp_f32_e32 v85, v85
	s_waitcnt lgkmcnt(6)
	v_mfma_f32_32x32x16_bf16 v[32:47], v[206:209], v[104:107], v[32:47]
	ds_read_b128 v[206:209], v169 offset:31296
	s_waitcnt vmcnt(1)
	ds_write_b128 v185, v[132:135] offset:17408
	v_exp_f32_e32 v86, v86
	v_exp_f32_e32 v87, v87
	v_cvt_pk_bf16_f32 v80, v80, v81
	s_waitcnt lgkmcnt(7)
	v_mfma_f32_32x32x16_bf16 v[16:31], v[210:213], v[104:107], v[16:31]
	ds_read_b128 v[210:213], v169 offset:17504
	s_waitcnt vmcnt(0)
	ds_write_b128 v218, v[136:139] offset:17408
	v_cvt_pk_bf16_f32 v81, v82, v83
	v_cvt_pk_bf16_f32 v82, v84, v85
	v_cvt_pk_bf16_f32 v83, v86, v87
	s_waitcnt lgkmcnt(8)
	v_mfma_f32_32x32x16_bf16 v[0:15], v[214:217], v[104:107], v[0:15]
	ds_read_b128 v[214:217], v169 offset:22112
	s_waitcnt lgkmcnt(1)
	s_barrier
	s_add_i32 s22, s10, 64
	s_cmpk_eq_i32 s22, 0x2000
	s_cbranch_scc1 .Lfar_p2_tailnp
	s_add_i32 s24, s21, s22
	s_addk_i32 s24, 0x99
	s_cmpk_gt_u32 s24, 0x112
	s_cbranch_scc0 .Lfar_p2_tailnp
	s_cmpk_gt_u32 s11, 0x7d
	s_cbranch_scc1 .Lfar_p2_noloada
	global_load_dwordx4 v[128:131], v[174:175], off
	global_load_dwordx4 v[132:135], v[172:173], off
	global_load_dwordx4 v[136:139], v[170:171], off
.Lfar_p2_noloada:
	v_mfma_f32_16x16x32_bf16 v[248:251], v[226:229], v[80:83], v[248:251]
	v_exp_f32_e32 v88, v88
	v_exp_f32_e32 v89, v89
	v_exp_f32_e32 v90, v90
	v_mfma_f32_32x32x16_bf16 v[48:63], v[230:233], v[80:83], v[48:63]
	ds_read_b128 v[230:233], v169 offset:26720
	v_exp_f32_e32 v91, v91
	v_exp_f32_e32 v92, v92
	v_exp_f32_e32 v93, v93
	v_mfma_f32_32x32x16_bf16 v[32:47], v[236:239], v[80:83], v[32:47]
	ds_read_b128 v[236:239], v169 offset:31328
	v_exp_f32_e32 v94, v94
	v_exp_f32_e32 v95, v95
	v_cvt_pk_bf16_f32 v88, v88, v89
	v_mfma_f32_32x32x16_bf16 v[16:31], v[178:181], v[80:83], v[16:31]
	v_add_u32_e32 v169, s12, v198
	ds_read_b128 v[178:181], v169
	v_cvt_pk_bf16_f32 v89, v90, v91
	v_cvt_pk_bf16_f32 v90, v92, v93
	v_cvt_pk_bf16_f32 v91, v94, v95
	v_mfma_f32_32x32x16_bf16 v[0:15], v[206:209], v[80:83], v[0:15]
	ds_read_b128 v[206:209], v169 offset:32
	v_mfma_f32_16x16x32_bf16 v[248:251], v[226:229], v[88:91], v[248:251]
	s_add_i32 s10, s10, 64
	s_add_i32 s11, s11, 1
	v_mfma_f32_32x32x16_bf16 v[48:63], v[210:213], v[88:91], v[48:63]
	ds_read_b128 v[210:213], v169 offset:64
	v_lshl_add_u64 v[170:171], v[170:171], 0, s[72:73]
	s_waitcnt lgkmcnt(5)
	v_mfma_f32_32x32x16_bf16 v[32:47], v[214:217], v[88:91], v[32:47]
	ds_read_b128 v[214:217], v169 offset:96
	v_lshl_add_u64 v[172:173], v[172:173], 0, s[72:73]
	s_waitcnt lgkmcnt(5)
	v_mfma_f32_32x32x16_bf16 v[16:31], v[230:233], v[88:91], v[16:31]
	ds_read_b128 v[230:233], v169 offset:4608
	v_lshl_add_u64 v[174:175], v[174:175], 0, s[0:1]
	s_mov_b32 s13, s12
	s_waitcnt lgkmcnt(5)
	v_mfma_f32_32x32x16_bf16 v[0:15], v[236:239], v[88:91], v[0:15]
	ds_read_b128 v[236:239], v169 offset:4640
	s_add_i32 s12, s13, 0x8c00
	s_cmp_lg_u32 s13, 0x11800
	s_cselect_b32 s12, s12, 0
	s_cmp_gt_i32 s24, -1
	s_cselect_b64 vcc, -1, 0
	s_nop 1
	v_cndmask_b32_e32 v80, v204, v205, vcc
	v_mov_b32_e32 v81, v80
	v_mov_b32_e32 v82, v80
	v_mov_b32_e32 v83, v80
	v_mov_b32_e32 v84, v80
	v_mov_b32_e32 v85, v80
	v_mov_b32_e32 v86, v80
	v_mov_b32_e32 v87, v80
	v_mov_b32_e32 v88, v80
	v_mov_b32_e32 v89, v80
	v_mov_b32_e32 v90, v80
	v_mov_b32_e32 v91, v80
	v_mov_b32_e32 v92, v80
	v_mov_b32_e32 v93, v80
	v_mov_b32_e32 v94, v80
	v_mov_b32_e32 v95, v80
	s_nop 0
	s_branch .Lfar_p2_main
.Lfar_p2_tailnp:
	s_cmpk_gt_u32 s11, 0x7d
	s_cbranch_scc1 .Lfar_p2_noloadb
	global_load_dwordx4 v[128:131], v[174:175], off
	global_load_dwordx4 v[132:135], v[172:173], off
	global_load_dwordx4 v[136:139], v[170:171], off
.Lfar_p2_noloadb:
	v_mfma_f32_16x16x32_bf16 v[248:251], v[226:229], v[80:83], v[248:251]
	v_exp_f32_e32 v88, v88
	v_exp_f32_e32 v89, v89
	v_exp_f32_e32 v90, v90
	v_mfma_f32_32x32x16_bf16 v[48:63], v[230:233], v[80:83], v[48:63]
	ds_read_b128 v[230:233], v169 offset:26720
	v_exp_f32_e32 v91, v91
	v_exp_f32_e32 v92, v92
	v_exp_f32_e32 v93, v93
	v_mfma_f32_32x32x16_bf16 v[32:47], v[236:239], v[80:83], v[32:47]
	ds_read_b128 v[236:239], v169 offset:31328
	v_exp_f32_e32 v94, v94
	v_exp_f32_e32 v95, v95
	v_cvt_pk_bf16_f32 v88, v88, v89
	v_mfma_f32_32x32x16_bf16 v[16:31], v[178:181], v[80:83], v[16:31]
	v_cvt_pk_bf16_f32 v89, v90, v91
	v_cvt_pk_bf16_f32 v90, v92, v93
	v_cvt_pk_bf16_f32 v91, v94, v95
	v_mfma_f32_32x32x16_bf16 v[0:15], v[206:209], v[80:83], v[0:15]
	v_mfma_f32_16x16x32_bf16 v[248:251], v[226:229], v[88:91], v[248:251]
	s_add_i32 s10, s10, 64
	s_add_i32 s11, s11, 1
	v_mfma_f32_32x32x16_bf16 v[48:63], v[210:213], v[88:91], v[48:63]
	v_lshl_add_u64 v[170:171], v[170:171], 0, s[72:73]
	s_waitcnt lgkmcnt(2)
	v_mfma_f32_32x32x16_bf16 v[32:47], v[214:217], v[88:91], v[32:47]
	v_lshl_add_u64 v[172:173], v[172:173], 0, s[72:73]
	s_waitcnt lgkmcnt(1)
	v_mfma_f32_32x32x16_bf16 v[16:31], v[230:233], v[88:91], v[16:31]
	v_lshl_add_u64 v[174:175], v[174:175], 0, s[0:1]
	s_mov_b32 s13, s12
	s_waitcnt lgkmcnt(0)
	v_mfma_f32_32x32x16_bf16 v[0:15], v[236:239], v[88:91], v[0:15]
	s_cmpk_lg_i32 s10, 0x2000
	s_cbranch_scc0 .LBB0_1019
	s_branch .LBB0_1060

.Lgqa_main:
	v_mfma_f32_16x16x32_bf16 v[96:99], v[244:247], v[64:67], v[96:99]
	v_exp_f32_e32 v72, v72
	v_exp_f32_e32 v73, v73
	v_exp_f32_e32 v74, v74
	s_waitcnt lgkmcnt(3)
	v_mfma_f32_32x32x16_bf16 v[0:15], v[226:229], v[64:67], v[0:15]
	ds_read_b128 v[226:229], v248 offset:17472
	v_exp_f32_e32 v75, v75
	v_exp_f32_e32 v76, v76
	v_exp_f32_e32 v77, v77
	v_cvt_pk_bf16_f32 v72, v72, v73
	s_waitcnt lgkmcnt(3)
	v_mfma_f32_32x32x16_bf16 v[16:31], v[230:233], v[64:67], v[16:31]
	ds_read_b128 v[230:233], v248 offset:22080
	v_exp_f32_e32 v78, v78
	v_exp_f32_e32 v79, v79
	v_cvt_pk_bf16_f32 v73, v74, v75
	v_cvt_pk_bf16_f32 v74, v76, v77
	v_cvt_pk_bf16_f32 v75, v78, v79
	s_nop 1
	v_mfma_f32_16x16x32_bf16 v[96:99], v[244:247], v[72:75], v[96:99]
	v_exp_f32_e32 v80, v80
	v_exp_f32_e32 v81, v81
	v_exp_f32_e32 v82, v82
	s_waitcnt lgkmcnt(3)
	v_mfma_f32_32x32x16_bf16 v[0:15], v[236:239], v[72:75], v[0:15]
	ds_read_b128 v[236:239], v248 offset:17504
	v_add3_u32 v249, s4, v193, v212
	v_add3_u32 v250, s4, v213, v214
	s_waitcnt vmcnt(1)
	ds_write_b128 v249, v[152:155]
	v_exp_f32_e32 v83, v83
	v_exp_f32_e32 v84, v84
	v_exp_f32_e32 v85, v85
	v_cvt_pk_bf16_f32 v80, v80, v81
	s_waitcnt lgkmcnt(4)
	v_mfma_f32_32x32x16_bf16 v[16:31], v[240:243], v[72:75], v[16:31]
	ds_read_b128 v[240:243], v248 offset:22112
	s_waitcnt vmcnt(0)
	ds_write_b128 v250, v[160:163] offset:17408
	v_exp_f32_e32 v86, v86
	v_exp_f32_e32 v87, v87
	v_cvt_pk_bf16_f32 v81, v82, v83
	v_cvt_pk_bf16_f32 v82, v84, v85
	v_cvt_pk_bf16_f32 v83, v86, v87
	s_nop 1
	s_waitcnt lgkmcnt(0)
	s_barrier
	s_cmpk_eq_i32 s23, 0x7f
	s_cbranch_scc1 .Lgqa_last
	s_cmpk_gt_u32 s23, 0x7d
	s_cbranch_scc1 .Lgqa_noloada
	global_load_dwordx4 v[152:155], v[210:211], off
	global_load_dwordx4 v[160:163], v[208:209], off
.Lgqa_noloada:
	s_mov_b64 s[14:15], 0x60000
	s_mov_b64 s[16:17], 0x80
	v_mfma_f32_16x16x32_bf16 v[96:99], v[244:247], v[80:83], v[96:99]
	v_exp_f32_e32 v88, v88
	v_exp_f32_e32 v89, v89
	v_exp_f32_e32 v90, v90
	v_mfma_f32_32x32x16_bf16 v[0:15], v[226:229], v[80:83], v[0:15]
	v_add_u32_e32 v248, s4, v217
	ds_read_b128 v[226:229], v248
	v_exp_f32_e32 v91, v91
	v_exp_f32_e32 v92, v92
	v_exp_f32_e32 v93, v93
	v_cvt_pk_bf16_f32 v88, v88, v89
	v_mfma_f32_32x32x16_bf16 v[16:31], v[230:233], v[80:83], v[16:31]
	ds_read_b128 v[230:233], v248 offset:32
	v_exp_f32_e32 v94, v94
	v_exp_f32_e32 v95, v95
	v_cvt_pk_bf16_f32 v89, v90, v91
	v_cvt_pk_bf16_f32 v90, v92, v93
	v_cvt_pk_bf16_f32 v91, v94, v95
	s_nop 1
	v_mfma_f32_16x16x32_bf16 v[96:99], v[244:247], v[88:91], v[96:99]
	s_add_i32 s23, s23, 1
	v_lshl_add_u64 v[210:211], v[210:211], 0, s[14:15]
	v_mfma_f32_32x32x16_bf16 v[0:15], v[236:239], v[88:91], v[0:15]
	ds_read_b128 v[236:239], v248 offset:64
	v_lshl_add_u64 v[208:209], v[208:209], 0, s[16:17]
	v_mfma_f32_32x32x16_bf16 v[16:31], v[240:243], v[88:91], v[16:31]
	ds_read_b128 v[240:243], v248 offset:96
	s_mov_b32 s21, s4
	s_add_i32 s4, s21, 0x8c00
	s_cmp_lg_u32 s21, 0x11800
	s_cselect_b32 s4, s4, 0
	s_waitcnt lgkmcnt(3)
	v_mfma_f32_32x32x16_bf16 v[64:79], v[226:229], v[144:147], v[48:63]
	ds_read_b128 v[226:229], v248 offset:4608
	s_waitcnt lgkmcnt(3)
	v_mfma_f32_32x32x16_bf16 v[64:79], v[230:233], v[148:151], v[64:79]
	ds_read_b128 v[230:233], v248 offset:4640
	s_waitcnt lgkmcnt(3)
	v_mfma_f32_32x32x16_bf16 v[64:79], v[236:239], v[156:159], v[64:79]
	ds_read_b128 v[236:239], v248 offset:4672
	s_waitcnt lgkmcnt(3)
	v_mfma_f32_32x32x16_bf16 v[64:79], v[240:243], v[164:167], v[64:79]
	ds_read_b128 v[240:243], v248 offset:4704
	s_waitcnt lgkmcnt(3)
	v_mfma_f32_32x32x16_bf16 v[80:95], v[226:229], v[144:147], v[48:63]
	ds_read_b128 v[226:229], v248 offset:17408
	s_waitcnt lgkmcnt(3)
	v_mfma_f32_32x32x16_bf16 v[80:95], v[230:233], v[148:151], v[80:95]
	ds_read_b128 v[230:233], v248 offset:22016
	s_nop 4
	v_exp_f32_e32 v64, v64
	v_exp_f32_e32 v65, v65
	v_exp_f32_e32 v66, v66
	s_waitcnt lgkmcnt(3)
	v_mfma_f32_32x32x16_bf16 v[80:95], v[236:239], v[156:159], v[80:95]
	ds_read_b128 v[236:239], v248 offset:17440
	v_exp_f32_e32 v67, v67
	v_exp_f32_e32 v68, v68
	v_exp_f32_e32 v69, v69
	s_waitcnt lgkmcnt(3)
	v_mfma_f32_32x32x16_bf16 v[80:95], v[240:243], v[164:167], v[80:95]
	ds_read_b128 v[240:243], v248 offset:22048
	v_exp_f32_e32 v70, v70
	v_exp_f32_e32 v71, v71
	v_cvt_pk_bf16_f32 v64, v64, v65
	v_cvt_pk_bf16_f32 v65, v66, v67
	v_cvt_pk_bf16_f32 v66, v68, v69
	v_cvt_pk_bf16_f32 v67, v70, v71
	s_nop 1
	s_branch .Lgqa_main
.Lgqa_last:
	v_mfma_f32_16x16x32_bf16 v[96:99], v[244:247], v[80:83], v[96:99]
	v_exp_f32_e32 v88, v88
	v_exp_f32_e32 v89, v89
	v_exp_f32_e32 v90, v90
	v_mfma_f32_32x32x16_bf16 v[0:15], v[226:229], v[80:83], v[0:15]
	v_exp_f32_e32 v91, v91
	v_exp_f32_e32 v92, v92
	v_exp_f32_e32 v93, v93
	v_cvt_pk_bf16_f32 v88, v88, v89
	v_mfma_f32_32x32x16_bf16 v[16:31], v[230:233], v[80:83], v[16:31]
	v_exp_f32_e32 v94, v94
	v_exp_f32_e32 v95, v95
	v_cvt_pk_bf16_f32 v89, v90, v91
	v_cvt_pk_bf16_f32 v90, v92, v93
	v_cvt_pk_bf16_f32 v91, v94, v95
	s_nop 1
	v_mfma_f32_16x16x32_bf16 v[96:99], v[244:247], v[88:91], v[96:99]
	v_mfma_f32_32x32x16_bf16 v[0:15], v[236:239], v[88:91], v[0:15]
	v_mfma_f32_32x32x16_bf16 v[16:31], v[240:243], v[88:91], v[16:31]
	v_mbcnt_lo_u32_b32 v249, -1, 0
	v_mbcnt_hi_u32_b32 v249, -1, v249
	v_and_b32_e32 v250, 15, v249
	v_lshlrev_b32_e32 v250, 2, v250
	v_and_b32_e32 v249, 16, v249
	s_nop 3
	v_cmp_ne_u32_e32 vcc, 0, v249
	ds_bpermute_b32 v248, v250, v96
	ds_bpermute_b32 v250, v250, v97
	s_waitcnt lgkmcnt(0)
	v_cndmask_b32_e32 v96, v248, v250, vcc
	s_branch .LBB0_1232
